# attention softmax row-max reductions via v_permlane16/32_swap instead of ds_bpermute round trips
# speedup vs baseline: 1.0689x; 1.0003x over previous
.LBB0_99:
	s_waitcnt lgkmcnt(14)
	v_pk_add_f32 v[126:127], v[126:127], v[132:133]
	s_waitcnt lgkmcnt(2)
	v_mov_b32_e32 v139, v136
	v_pk_add_f32 v[214:215], v[128:129], v[140:141]
	v_pk_add_f32 v[114:115], v[114:115], v[142:143]
	v_pk_add_f32 v[142:143], v[110:111], v[154:155]
	v_pk_add_f32 v[110:111], v[100:101], v[206:207]
	v_pk_add_f32 v[100:101], v[102:103], v[138:139]
	v_max3_f32 v102, v126, s10, v127
	v_max3_f32 v102, v102, v214, v215
	v_pk_add_f32 v[116:117], v[116:117], v[156:157]
	v_max3_f32 v102, v102, v114, v115
	v_pk_add_f32 v[128:129], v[124:125], v[134:135]
	v_pk_add_f32 v[134:135], v[118:119], v[146:147]
	v_pk_add_f32 v[118:119], v[106:107], v[150:151]
	v_max3_f32 v102, v102, v116, v117
	v_pk_add_f32 v[108:109], v[108:109], v[160:161]
	v_max3_f32 v102, v102, v118, v119
	v_pk_add_f32 v[140:141], v[112:113], v[148:149]
	v_pk_add_f32 v[112:113], v[98:99], v[158:159]
	v_max3_f32 v102, v102, v108, v109
	v_max3_f32 v102, v102, v112, v113
	v_max3_f32 v102, v102, v110, v111
	v_mov_b32_e32 v103, v102
	s_nop 1
	v_permlane16_swap_b32_e32 v102, v103
	v_pk_add_f32 v[132:133], v[120:121], v[144:145]
	v_pk_add_f32 v[130:131], v[122:123], v[130:131]
	s_waitcnt lgkmcnt(0)
	v_pk_add_f32 v[98:99], v[104:105], v[152:153]
	ds_read_b64_tr_b16 v[156:157], v197 offset:50432
	ds_read_b64_tr_b16 v[154:155], v197 offset:41984
	ds_read_b64_tr_b16 v[158:159], v197 offset:42016
	v_max_f32_e32 v102, v102, v103
	v_mov_b32_e32 v103, v102
	s_nop 1
	v_permlane32_swap_b32_e32 v102, v103
	v_max3_f32 v138, v181, v102, v103
	v_sub_f32_e32 v103, v126, v138
	v_exp_f32_e32 v107, v103
	v_sub_f32_e32 v103, v127, v138
	v_exp_f32_e32 v139, v103
	v_sub_f32_e32 v103, v214, v138
	v_exp_f32_e32 v144, v103
	v_sub_f32_e32 v103, v215, v138
	v_exp_f32_e32 v145, v103
	v_sub_f32_e32 v103, v114, v138
	v_exp_f32_e32 v146, v103
	v_sub_f32_e32 v103, v115, v138
	v_exp_f32_e32 v147, v103
	v_sub_f32_e32 v103, v116, v138
	v_sub_f32_e32 v102, v181, v138
	v_exp_f32_e32 v126, v103
	v_sub_f32_e32 v103, v117, v138
	v_exp_f32_e32 v124, v103
	v_sub_f32_e32 v103, v118, v138
	v_exp_f32_e32 v106, v102
	v_max3_f32 v102, v130, s10, v131
	v_exp_f32_e32 v122, v103
	v_sub_f32_e32 v103, v119, v138
	v_max3_f32 v102, v102, v128, v129
	v_exp_f32_e32 v120, v103
	v_sub_f32_e32 v103, v108, v138
	v_max3_f32 v102, v102, v134, v135
	v_exp_f32_e32 v118, v103
	v_sub_f32_e32 v103, v109, v138
	v_max3_f32 v102, v102, v132, v133
	v_exp_f32_e32 v116, v103
	v_sub_f32_e32 v103, v112, v138
	v_max3_f32 v102, v102, v142, v143
	v_exp_f32_e32 v114, v103
	v_sub_f32_e32 v103, v113, v138
	v_max3_f32 v102, v102, v140, v141
	v_exp_f32_e32 v112, v103
	v_sub_f32_e32 v103, v110, v138
	v_max3_f32 v102, v102, v100, v101
	v_exp_f32_e32 v110, v103
	v_sub_f32_e32 v103, v111, v138
	v_max3_f32 v102, v102, v98, v99
	v_exp_f32_e32 v108, v103
	v_mov_b32_e32 v103, v102
	s_nop 1
	v_permlane16_swap_b32_e32 v102, v103
	v_pk_mul_f32 v[88:89], v[88:89], v[106:107] op_sel_hi:[1,0]
	v_pk_mul_f32 v[86:87], v[86:87], v[106:107] op_sel_hi:[1,0]
	v_pk_mul_f32 v[92:93], v[92:93], v[106:107] op_sel_hi:[1,0]
	v_pk_mul_f32 v[90:91], v[90:91], v[106:107] op_sel_hi:[1,0]
	v_max_f32_e32 v102, v102, v103
	v_mov_b32_e32 v103, v102
	s_nop 1
	v_permlane32_swap_b32_e32 v102, v103
	v_pk_mul_f32 v[84:85], v[84:85], v[106:107] op_sel_hi:[1,0]
	v_pk_mul_f32 v[82:83], v[82:83], v[106:107] op_sel_hi:[1,0]
	v_pk_mul_f32 v[96:97], v[96:97], v[106:107] op_sel_hi:[1,0]
	v_pk_mul_f32 v[94:95], v[94:95], v[106:107] op_sel_hi:[1,0]
	v_max3_f32 v148, v175, v102, v103
	v_sub_f32_e32 v103, v130, v148
	v_exp_f32_e32 v149, v103
	v_sub_f32_e32 v103, v131, v148
	v_exp_f32_e32 v150, v103
	v_sub_f32_e32 v103, v128, v148
	v_exp_f32_e32 v151, v103
	v_sub_f32_e32 v103, v129, v148
	v_exp_f32_e32 v129, v103
	v_sub_f32_e32 v103, v134, v148
	v_exp_f32_e32 v152, v103
	v_sub_f32_e32 v103, v135, v148
	v_exp_f32_e32 v153, v103
	v_sub_f32_e32 v103, v132, v148
	v_sub_f32_e32 v102, v175, v148
	v_exp_f32_e32 v127, v103
	v_sub_f32_e32 v103, v133, v148
	v_exp_f32_e32 v125, v103
	v_sub_f32_e32 v103, v142, v148
	v_exp_f32_e32 v128, v102
	v_exp_f32_e32 v123, v103
	v_sub_f32_e32 v103, v143, v148
	v_exp_f32_e32 v121, v103
	v_sub_f32_e32 v103, v140, v148
	v_sub_f32_e32 v100, v100, v148
	v_sub_f32_e32 v98, v98, v148
	v_exp_f32_e32 v119, v103
	v_sub_f32_e32 v103, v141, v148
	v_exp_f32_e32 v115, v100
	v_sub_f32_e32 v100, v101, v148
	v_exp_f32_e32 v111, v98
	v_sub_f32_e32 v98, v99, v148
	v_exp_f32_e32 v117, v103
	v_exp_f32_e32 v113, v100
	v_exp_f32_e32 v109, v98
	v_pk_mul_f32 v[24:25], v[24:25], v[128:129] op_sel_hi:[1,0]
	v_pk_mul_f32 v[22:23], v[22:23], v[128:129] op_sel_hi:[1,0]
	v_cvt_pk_bf16_f32 v130, v107, v139
	v_cvt_pk_bf16_f32 v131, v144, v145
	v_cvt_pk_bf16_f32 v132, v146, v147
	v_cvt_pk_bf16_f32 v133, v126, v124
	v_cvt_pk_bf16_f32 v140, v149, v150
	v_cvt_pk_bf16_f32 v141, v151, v129
	v_cvt_pk_bf16_f32 v142, v152, v153
	v_cvt_pk_bf16_f32 v143, v127, v125
	s_waitcnt lgkmcnt(0)
	v_mfma_f32_16x16x32_bf16 v[86:89], v[154:157], v[130:133], v[86:89]
	v_mul_f32_e64 v104, v80, v128
	v_mul_f32_e64 v105, v81, v128
	v_pk_mul_f32 v[102:103], v[78:79], v[128:129] op_sel_hi:[1,0]
	v_cvt_pk_bf16_f32 v78, v122, v120
	v_mfma_f32_16x16x32_bf16 v[22:25], v[154:157], v[140:143], v[22:25]
	ds_read_b64_tr_b16 v[154:155], v197 offset:58880
	ds_read_b64_tr_b16 v[156:157], v199 offset:25344
	ds_read_b64_tr_b16 v[244:245], v199 offset:25376
	v_cvt_pk_bf16_f32 v79, v118, v116
	v_cvt_pk_bf16_f32 v80, v114, v112
	v_cvt_pk_bf16_f32 v81, v110, v108
	v_cvt_pk_bf16_f32 v98, v123, v121
	v_cvt_pk_bf16_f32 v99, v119, v117
	v_cvt_pk_bf16_f32 v100, v115, v113
	v_cvt_pk_bf16_f32 v101, v111, v109
	s_waitcnt lgkmcnt(1)
	v_mfma_f32_16x16x32_bf16 v[86:89], v[154:157], v[78:81], v[86:89]
	ds_read_b64_tr_b16 v[160:161], v197 offset:50464
	ds_read_b64_tr_b16 v[242:243], v197 offset:58912
	v_pk_mul_f32 v[44:45], v[44:45], v[128:129] op_sel_hi:[1,0]
	v_mfma_f32_16x16x32_bf16 v[22:25], v[154:157], v[98:101], v[22:25]
	ds_read_b64_tr_b16 v[154:155], v197 offset:42048
	ds_read_b64_tr_b16 v[156:157], v197 offset:50496
	v_pk_mul_f32 v[42:43], v[42:43], v[128:129] op_sel_hi:[1,0]
	v_pk_mul_f32 v[20:21], v[20:21], v[128:129] op_sel_hi:[1,0]
	s_waitcnt lgkmcnt(0)
	v_mfma_f32_16x16x32_bf16 v[90:93], v[154:157], v[130:133], v[90:93]
	v_mul_f32_e64 v18, v18, v128
	v_mul_f32_e64 v19, v19, v128
	v_mfma_f32_16x16x32_bf16 v[42:45], v[154:157], v[140:143], v[42:45]
	ds_read_b64_tr_b16 v[154:155], v197 offset:58944
	ds_read_b64_tr_b16 v[156:157], v199 offset:25408
	s_waitcnt lgkmcnt(0)
	v_mfma_f32_16x16x32_bf16 v[90:93], v[154:157], v[78:81], v[90:93]
	v_mfma_f32_16x16x32_bf16 v[42:45], v[154:157], v[98:101], v[42:45]
	ds_read_b64_tr_b16 v[154:155], v197 offset:42080
	ds_read_b64_tr_b16 v[156:157], v197 offset:50528
	v_mfma_f32_16x16x32_bf16 v[82:85], v[158:161], v[130:133], v[82:85]
	s_waitcnt lgkmcnt(0)
	v_mfma_f32_16x16x32_bf16 v[94:97], v[154:157], v[130:133], v[94:97]
	ds_read_b64_tr_b16 v[130:131], v197 offset:58976
	ds_read_b64_tr_b16 v[132:133], v199 offset:25440
	v_mfma_f32_16x16x32_bf16 v[18:21], v[158:161], v[140:143], v[18:21]
	v_mfma_f32_16x16x32_bf16 v[102:105], v[154:157], v[140:143], v[102:105]
	v_mfma_f32_16x16x32_bf16 v[82:85], v[242:245], v[78:81], v[82:85]
	v_mfma_f32_16x16x32_bf16 v[18:21], v[242:245], v[98:101], v[18:21]
	s_waitcnt lgkmcnt(0)
	v_mfma_f32_16x16x32_bf16 v[94:97], v[130:133], v[78:81], v[94:97]
	v_mfma_f32_16x16x32_bf16 v[78:81], v[130:133], v[98:101], v[102:105]
	s_cmp_lg_u32 s88, 0
	s_cbranch_scc1 .Lsc_noscan
	s_waitcnt vmcnt(0)
	s_cmp_ge_u32 s89, 8
	s_cbranch_scc1 .Lsc_noscan
	s_and_b32 s70, s89, 1
	s_lshl_b32 s70, s70, 12
	v_add_u32_e32 v247, s70, v246
	ds_read_b32 v2, v247
	ds_read_b32 v3, v247 offset:256
	ds_read_b32 v4, v247 offset:512
	ds_read_b32 v5, v247 offset:768
	ds_read_b32 v6, v247 offset:1024
	ds_read_b32 v7, v247 offset:1280
	ds_read_b32 v8, v247 offset:1536
	ds_read_b32 v9, v247 offset:1792
	ds_read_b32 v10, v247 offset:2048
	ds_read_b32 v11, v247 offset:2304
	ds_read_b32 v12, v247 offset:2560
	ds_read_b32 v13, v247 offset:2816
	ds_read_b32 v14, v247 offset:3072
	ds_read_b32 v15, v247 offset:3328
	ds_read_b32 v16, v247 offset:3584
	ds_read_b32 v17, v247 offset:3840
	s_lshl_b32 s70, s89, 21
	s_mov_b32 s71, 0
	v_lshl_add_u64 v[98:99], s[70:71], 0, v[166:167]
	s_mov_b32 s100, 0x20000
	s_mov_b32 s101, 0
	s_waitcnt lgkmcnt(0)
	v_readlane_b32 s70, v241, 0
	v_cvt_pk_bf16_f32 v100, v177, v176
	global_store_dword v[98:99], v100, off
	v_lshlrev_b32_e32 v101, 16, v2
	v_and_b32_e32 v102, 0xffff0000, v2
	v_readlane_b32 s71, v241, 1
	v_fma_f32 v177, v177, s70, v101
	v_fma_f32 v176, v176, s70, v102
	v_lshl_add_u64 v[98:99], v[98:99], 0, s[100:101]
	v_cvt_pk_bf16_f32 v100, v177, v176
	global_store_dword v[98:99], v100, off
	v_lshlrev_b32_e32 v101, 16, v3
	v_and_b32_e32 v102, 0xffff0000, v3
	v_readlane_b32 s70, v241, 2
	v_fma_f32 v177, v177, s71, v101
	v_fma_f32 v176, v176, s71, v102
	v_lshl_add_u64 v[98:99], v[98:99], 0, s[100:101]
	v_cvt_pk_bf16_f32 v100, v177, v176
	global_store_dword v[98:99], v100, off
	v_lshlrev_b32_e32 v101, 16, v4
	v_and_b32_e32 v102, 0xffff0000, v4
	v_readlane_b32 s71, v241, 3
	v_fma_f32 v177, v177, s70, v101
	v_fma_f32 v176, v176, s70, v102
	v_lshl_add_u64 v[98:99], v[98:99], 0, s[100:101]
	v_cvt_pk_bf16_f32 v100, v177, v176
	global_store_dword v[98:99], v100, off
	v_lshlrev_b32_e32 v101, 16, v5
	v_and_b32_e32 v102, 0xffff0000, v5
	v_readlane_b32 s70, v241, 4
	v_fma_f32 v177, v177, s71, v101
	v_fma_f32 v176, v176, s71, v102
	v_lshl_add_u64 v[98:99], v[98:99], 0, s[100:101]
	v_cvt_pk_bf16_f32 v100, v177, v176
	global_store_dword v[98:99], v100, off
	v_lshlrev_b32_e32 v101, 16, v6
	v_and_b32_e32 v102, 0xffff0000, v6
	v_readlane_b32 s71, v241, 5
	v_fma_f32 v177, v177, s70, v101
	v_fma_f32 v176, v176, s70, v102
	v_lshl_add_u64 v[98:99], v[98:99], 0, s[100:101]
	v_cvt_pk_bf16_f32 v100, v177, v176
	global_store_dword v[98:99], v100, off
	v_lshlrev_b32_e32 v101, 16, v7
	v_and_b32_e32 v102, 0xffff0000, v7
	v_readlane_b32 s70, v241, 6
	v_fma_f32 v177, v177, s71, v101
	v_fma_f32 v176, v176, s71, v102
	v_lshl_add_u64 v[98:99], v[98:99], 0, s[100:101]
	v_cvt_pk_bf16_f32 v100, v177, v176
	global_store_dword v[98:99], v100, off
	v_lshlrev_b32_e32 v101, 16, v8
	v_and_b32_e32 v102, 0xffff0000, v8
	v_readlane_b32 s71, v241, 7
	v_fma_f32 v177, v177, s70, v101
	v_fma_f32 v176, v176, s70, v102
	v_lshl_add_u64 v[98:99], v[98:99], 0, s[100:101]
	v_cvt_pk_bf16_f32 v100, v177, v176
	global_store_dword v[98:99], v100, off
	v_lshlrev_b32_e32 v101, 16, v9
	v_and_b32_e32 v102, 0xffff0000, v9
	v_readlane_b32 s70, v241, 8
	v_fma_f32 v177, v177, s71, v101
	v_fma_f32 v176, v176, s71, v102
	v_lshl_add_u64 v[98:99], v[98:99], 0, s[100:101]
	v_cvt_pk_bf16_f32 v100, v177, v176
	global_store_dword v[98:99], v100, off
	v_lshlrev_b32_e32 v101, 16, v10
	v_and_b32_e32 v102, 0xffff0000, v10
	v_readlane_b32 s71, v241, 9
	v_fma_f32 v177, v177, s70, v101
	v_fma_f32 v176, v176, s70, v102
	v_lshl_add_u64 v[98:99], v[98:99], 0, s[100:101]
	v_cvt_pk_bf16_f32 v100, v177, v176
	global_store_dword v[98:99], v100, off
	v_lshlrev_b32_e32 v101, 16, v11
	v_and_b32_e32 v102, 0xffff0000, v11
	v_readlane_b32 s70, v241, 10
	v_fma_f32 v177, v177, s71, v101
	v_fma_f32 v176, v176, s71, v102
	v_lshl_add_u64 v[98:99], v[98:99], 0, s[100:101]
	v_cvt_pk_bf16_f32 v100, v177, v176
	global_store_dword v[98:99], v100, off
	v_lshlrev_b32_e32 v101, 16, v12
	v_and_b32_e32 v102, 0xffff0000, v12
	v_readlane_b32 s71, v241, 11
	v_fma_f32 v177, v177, s70, v101
	v_fma_f32 v176, v176, s70, v102
	v_lshl_add_u64 v[98:99], v[98:99], 0, s[100:101]
	v_cvt_pk_bf16_f32 v100, v177, v176
	global_store_dword v[98:99], v100, off
	v_lshlrev_b32_e32 v101, 16, v13
	v_and_b32_e32 v102, 0xffff0000, v13
	v_readlane_b32 s70, v241, 12
	v_fma_f32 v177, v177, s71, v101
	v_fma_f32 v176, v176, s71, v102
	v_lshl_add_u64 v[98:99], v[98:99], 0, s[100:101]
	v_cvt_pk_bf16_f32 v100, v177, v176
	global_store_dword v[98:99], v100, off
	v_lshlrev_b32_e32 v101, 16, v14
	v_and_b32_e32 v102, 0xffff0000, v14
	v_readlane_b32 s71, v241, 13
	v_fma_f32 v177, v177, s70, v101
	v_fma_f32 v176, v176, s70, v102
	v_lshl_add_u64 v[98:99], v[98:99], 0, s[100:101]
	v_cvt_pk_bf16_f32 v100, v177, v176
	global_store_dword v[98:99], v100, off
	v_lshlrev_b32_e32 v101, 16, v15
	v_and_b32_e32 v102, 0xffff0000, v15
	v_readlane_b32 s70, v241, 14
	v_fma_f32 v177, v177, s71, v101
	v_fma_f32 v176, v176, s71, v102
	v_lshl_add_u64 v[98:99], v[98:99], 0, s[100:101]
	v_cvt_pk_bf16_f32 v100, v177, v176
	global_store_dword v[98:99], v100, off
	v_lshlrev_b32_e32 v101, 16, v16
	v_and_b32_e32 v102, 0xffff0000, v16
	v_readlane_b32 s71, v241, 15
	v_fma_f32 v177, v177, s70, v101
	v_fma_f32 v176, v176, s70, v102
	v_lshl_add_u64 v[98:99], v[98:99], 0, s[100:101]
	v_cvt_pk_bf16_f32 v100, v177, v176
	global_store_dword v[98:99], v100, off
	v_lshlrev_b32_e32 v101, 16, v17
	v_and_b32_e32 v102, 0xffff0000, v17
	v_fma_f32 v177, v177, s71, v101
	v_fma_f32 v176, v176, s71, v102
